# v25 + P9 phase (b) winner extraction: sixteen LDS read-wait-write round trips batched into sixteen reads, one wait, sixteen writes
# speedup vs baseline: 1.0014x; 1.0014x over previous
; #define LAS __attribute__((address_space(3)))
; __device__ __forceinline__ void peer_score_unit(const Frame& F, int l, int unit) {
;     ...
;         for (int tb = 0; tb < 2; ++tb) {
;             f32x16 acc;
; #pragma unroll
;             for (int i = 0; i < 16; ++i) acc[i] = 0.f;
; #pragma unroll
;             for (int ks = 0; ks < 8; ++ks) acc = __builtin_amdgcn_mfma_f32_32x32x16_bf16(afr[tb][ks], bfr[ks], acc, 0, 0, 0);
; #pragma unroll
;             for (int i = 0; i < 16; ++i) { const int t = 32 * tb + (i & 3) + 8 * (i >> 2) + 4 * h; S[(cc * 64 + t) * 129 + 32 * nb + rl] = acc[i]; }
;         }
;     }
;     __syncthreads();
;     for (int repb = 0; repb < P9_REP_B; ++repb) {
;         const int row = tid >> 2, qd = tid & 3;
;         const LAS float* base = S + row * 129 + 32 * qd;
;         unsigned x[32];
; #pragma unroll
;         for (int j = 0; j < 32; ++j) { const unsigned u = __float_as_uint(base[j]); const unsigned o = (u & 0x80000000u) ? ~u : (u | 0x80000000u); x[j] = (o & ~127u) | (unsigned)(127 - (32 * qd + j)); }
.Lp9_nw0:
	s_nop 0
	v_mfma_f32_32x32x16_bf16 v[0:15], v[0:3], v[44:47], 0
	v_mfma_f32_32x32x16_bf16 v[0:15], v[108:111], v[40:43], v[0:15]
	v_mfma_f32_32x32x16_bf16 v[0:15], v[104:107], v[36:39], v[0:15]
	v_mfma_f32_32x32x16_bf16 v[0:15], v[100:103], v[32:35], v[0:15]
	v_mfma_f32_32x32x16_bf16 v[0:15], v[96:99], v[28:31], v[0:15]
	v_mfma_f32_32x32x16_bf16 v[0:15], v[92:95], v[16:19], v[0:15]
	v_mfma_f32_32x32x16_bf16 v[0:15], v[88:91], v[20:23], v[0:15]
	v_mfma_f32_32x32x16_bf16 v[0:15], v[84:87], v[24:27], v[0:15]
	s_nop 11
	ds_write2_b32 v51, v0, v1 offset1:129
	v_add_u32_e32 v0, 0x400, v51
	ds_write2_b32 v0, v2, v3 offset0:2 offset1:131
	v_add_u32_e32 v0, 0x1000, v51
	ds_write2_b32 v0, v4, v5 offset0:8 offset1:137
	v_add_u32_e32 v0, 0x1400, v51
	ds_write2_b32 v0, v6, v7 offset0:10 offset1:139
	v_add_u32_e32 v0, 0x2000, v51
	ds_write2_b32 v0, v8, v9 offset0:16 offset1:145
	v_add_u32_e32 v0, 0x2400, v51
	ds_write2_b32 v0, v10, v11 offset0:18 offset1:147
	v_add_u32_e32 v0, 0x3000, v51
	ds_write2_b32 v0, v12, v13 offset0:24 offset1:153
	v_add_u32_e32 v0, 0x3400, v51
	ds_write2_b32 v0, v14, v15 offset0:26 offset1:155
	v_mfma_f32_32x32x16_bf16 v[0:15], v[80:83], v[44:47], 0
	v_mfma_f32_32x32x16_bf16 v[0:15], v[76:79], v[40:43], v[0:15]
	v_mfma_f32_32x32x16_bf16 v[0:15], v[72:75], v[36:39], v[0:15]
	v_mfma_f32_32x32x16_bf16 v[0:15], v[68:71], v[32:35], v[0:15]
	v_mfma_f32_32x32x16_bf16 v[0:15], v[64:67], v[28:31], v[0:15]
	v_mfma_f32_32x32x16_bf16 v[0:15], v[60:63], v[16:19], v[0:15]
	v_add_u32_e32 v16, 0x4000, v51
	v_mfma_f32_32x32x16_bf16 v[0:15], v[56:59], v[20:23], v[0:15]
	v_mfma_f32_32x32x16_bf16 v[0:15], v[52:55], v[24:27], v[0:15]
	s_nop 11
	ds_write2_b32 v16, v0, v1 offset0:32 offset1:161
	v_add_u32_e32 v0, 0x4400, v51
	ds_write2_b32 v0, v2, v3 offset0:34 offset1:163
	v_add_u32_e32 v0, 0x5000, v51
	ds_write2_b32 v0, v4, v5 offset0:40 offset1:169
	v_add_u32_e32 v0, 0x5400, v51
	ds_write2_b32 v0, v6, v7 offset0:42 offset1:171
	v_add_u32_e32 v0, 0x6000, v51
	ds_write2_b32 v0, v8, v9 offset0:48 offset1:177
	v_add_u32_e32 v0, 0x6400, v51
	ds_write2_b32 v0, v10, v11 offset0:50 offset1:179
	v_add_u32_e32 v0, 0x7000, v51
	ds_write2_b32 v0, v12, v13 offset0:56 offset1:185
	v_add_u32_e32 v0, 0x7400, v51
	v_ashrrev_i32_e32 v1, 2, v50
	ds_write2_b32 v0, v14, v15 offset0:58 offset1:187
	v_mul_lo_u32 v0, v1, s33
	v_and_b32_e32 v4, 3, v50
	v_add_u32_e32 v0, 0, v0
	v_lshl_add_u32 v3, v4, 7, v0
	s_waitcnt lgkmcnt(0)
	s_barrier
	v_lshlrev_b32_e32 v2, 5, v4
	v_cmp_eq_u32_e32 vcc, 0, v4
	ds_read2_b32 v[4:5], v3 offset1:1
	s_waitcnt lgkmcnt(0)
	v_not_b32_e32 v6, v4
	v_cmp_gt_i32_e64 s[0:1], 0, v4
	s_nop 1
	v_cndmask_b32_e64 v4, -|v4|, v6, s[0:1]
	v_and_b32_e32 v4, 0xffffff80, v4
	s_movk_i32 s0, 0x7f
	v_bitop3_b32 v4, v4, s0, v2 bitop3:0x36
	v_not_b32_e32 v6, v5
	v_cmp_gt_i32_e64 s[0:1], 0, v5
	s_nop 1
	v_cndmask_b32_e64 v5, -|v5|, v6, s[0:1]
	ds_read2_b32 v[6:7], v3 offset0:2 offset1:3
	v_and_b32_e32 v5, 0xffffff80, v5
	v_sub_u32_e32 v5, v5, v2
	v_add_u32_e32 v5, 0x7e, v5
	s_waitcnt lgkmcnt(0)
	v_not_b32_e32 v8, v6
	v_cmp_gt_i32_e64 s[0:1], 0, v6
	s_nop 1
	v_cndmask_b32_e64 v6, -|v6|, v8, s[0:1]
	v_not_b32_e32 v8, v7
	v_cmp_gt_i32_e64 s[0:1], 0, v7
	v_and_b32_e32 v6, 0xffffff80, v6
	v_sub_u32_e32 v6, v6, v2
	v_cndmask_b32_e64 v7, -|v7|, v8, s[0:1]
	ds_read2_b32 v[8:9], v3 offset0:4 offset1:5
	v_and_b32_e32 v7, 0xffffff80, v7
	v_sub_u32_e32 v7, v7, v2
	v_add_u32_e32 v6, 0x7d, v6
	v_add_u32_e32 v7, 0x7c, v7
	s_waitcnt lgkmcnt(0)
	v_not_b32_e32 v10, v8
	v_cmp_gt_i32_e64 s[0:1], 0, v8
	s_nop 1
	v_cndmask_b32_e64 v8, -|v8|, v10, s[0:1]
	v_not_b32_e32 v10, v9
	v_cmp_gt_i32_e64 s[0:1], 0, v9
	v_and_b32_e32 v8, 0xffffff80, v8
	v_sub_u32_e32 v8, v8, v2
	v_cndmask_b32_e64 v9, -|v9|, v10, s[0:1]
	ds_read2_b32 v[10:11], v3 offset0:6 offset1:7
	v_and_b32_e32 v9, 0xffffff80, v9
	v_sub_u32_e32 v9, v9, v2
	v_add_u32_e32 v8, 0x7b, v8
	v_add_u32_e32 v9, 0x7a, v9
	s_waitcnt lgkmcnt(0)
	v_not_b32_e32 v12, v10
	v_cmp_gt_i32_e64 s[0:1], 0, v10
	s_nop 1
	v_cndmask_b32_e64 v10, -|v10|, v12, s[0:1]
	v_not_b32_e32 v12, v11
	v_cmp_gt_i32_e64 s[0:1], 0, v11
	v_and_b32_e32 v10, 0xffffff80, v10
	v_sub_u32_e32 v10, v10, v2
	v_cndmask_b32_e64 v11, -|v11|, v12, s[0:1]
	ds_read2_b32 v[12:13], v3 offset0:8 offset1:9
	v_and_b32_e32 v11, 0xffffff80, v11
	v_sub_u32_e32 v11, v11, v2
	v_add_u32_e32 v10, 0x79, v10
	v_add_u32_e32 v11, 0x78, v11
	s_waitcnt lgkmcnt(0)
	v_not_b32_e32 v14, v12
	v_cmp_gt_i32_e64 s[0:1], 0, v12
	s_nop 1
	v_cndmask_b32_e64 v12, -|v12|, v14, s[0:1]
	v_not_b32_e32 v14, v13
	v_cmp_gt_i32_e64 s[0:1], 0, v13
	v_and_b32_e32 v12, 0xffffff80, v12
	v_sub_u32_e32 v12, v12, v2
	v_cndmask_b32_e64 v13, -|v13|, v14, s[0:1]
	ds_read2_b32 v[14:15], v3 offset0:10 offset1:11
	v_and_b32_e32 v13, 0xffffff80, v13
	v_sub_u32_e32 v13, v13, v2
	v_add_u32_e32 v12, 0x77, v12
	v_add_u32_e32 v13, 0x76, v13
	s_waitcnt lgkmcnt(0)
	v_not_b32_e32 v16, v14
	v_cmp_gt_i32_e64 s[0:1], 0, v14
	s_nop 1
	v_cndmask_b32_e64 v14, -|v14|, v16, s[0:1]
	v_not_b32_e32 v16, v15
	v_cmp_gt_i32_e64 s[0:1], 0, v15
	v_and_b32_e32 v14, 0xffffff80, v14
	v_sub_u32_e32 v14, v14, v2
	v_cndmask_b32_e64 v15, -|v15|, v16, s[0:1]
	ds_read2_b32 v[16:17], v3 offset0:12 offset1:13
	v_and_b32_e32 v15, 0xffffff80, v15
	v_sub_u32_e32 v15, v15, v2
	v_add_u32_e32 v14, 0x75, v14
	v_add_u32_e32 v15, 0x74, v15
	s_waitcnt lgkmcnt(0)
	v_not_b32_e32 v18, v16
	v_cmp_gt_i32_e64 s[0:1], 0, v16
	s_nop 1
	v_cndmask_b32_e64 v16, -|v16|, v18, s[0:1]
	v_not_b32_e32 v18, v17
	v_cmp_gt_i32_e64 s[0:1], 0, v17
	v_and_b32_e32 v16, 0xffffff80, v16
	v_sub_u32_e32 v16, v16, v2
	v_cndmask_b32_e64 v17, -|v17|, v18, s[0:1]
	ds_read2_b32 v[18:19], v3 offset0:14 offset1:15
	v_and_b32_e32 v17, 0xffffff80, v17
	v_sub_u32_e32 v17, v17, v2
	v_add_u32_e32 v16, 0x73, v16
	v_add_u32_e32 v17, 0x72, v17
	s_waitcnt lgkmcnt(0)
; #define CE_DESC(a_, b_) do { const unsigned hi_ = max(x[a_], x[b_]), lo_ = min(x[a_], x[b_]); x[a_] = hi_; x[b_] = lo_; } while (0)
; __device__ __forceinline__ void peer_score_unit(const Frame& F, int l, int unit) {
;     ...
;         unsigned x[32];
; #pragma unroll
;         for (int j = 0; j < 32; ++j) { const unsigned u = __float_as_uint(base[j]); const unsigned o = (u & 0x80000000u) ? ~u : (u | 0x80000000u); x[j] = (o & ~127u) | (unsigned)(127 - (32 * qd + j)); }
;     ...
; #pragma unroll
;         for (int k = 2; k <= 16; k <<= 1)
; #pragma unroll
;             for (int j = k >> 1; j > 0; j >>= 1)
; #pragma unroll
;                 for (int i = 0; i < 32; ++i) { const int l2 = i ^ j; if (l2 > i) { if ((i & k) == 0) CE_DESC(i, l2); else CE_DESC(l2, i); } }
	v_not_b32_e32 v20, v18
	v_cmp_gt_i32_e64 s[0:1], 0, v18
	s_nop 1
	v_cndmask_b32_e64 v18, -|v18|, v20, s[0:1]
	v_not_b32_e32 v20, v19
	v_cmp_gt_i32_e64 s[0:1], 0, v19
	v_and_b32_e32 v18, 0xffffff80, v18
	v_sub_u32_e32 v18, v18, v2
	v_cndmask_b32_e64 v19, -|v19|, v20, s[0:1]
	ds_read2_b32 v[20:21], v3 offset0:16 offset1:17
	v_and_b32_e32 v19, 0xffffff80, v19
	v_sub_u32_e32 v19, v19, v2
	v_add_u32_e32 v18, 0x71, v18
	v_add_u32_e32 v19, 0x70, v19
	s_waitcnt lgkmcnt(0)
	v_not_b32_e32 v22, v20
	v_cmp_gt_i32_e64 s[0:1], 0, v20
	s_nop 1
	v_cndmask_b32_e64 v20, -|v20|, v22, s[0:1]
	v_not_b32_e32 v22, v21
	v_cmp_gt_i32_e64 s[0:1], 0, v21
	v_and_b32_e32 v20, 0xffffff80, v20
	v_sub_u32_e32 v20, v20, v2
	v_cndmask_b32_e64 v21, -|v21|, v22, s[0:1]
	ds_read2_b32 v[22:23], v3 offset0:18 offset1:19
	v_and_b32_e32 v21, 0xffffff80, v21
	v_sub_u32_e32 v21, v21, v2
	v_add_u32_e32 v20, 0x6f, v20
	v_add_u32_e32 v21, 0x6e, v21
	s_waitcnt lgkmcnt(0)
	v_not_b32_e32 v24, v22
	v_cmp_gt_i32_e64 s[0:1], 0, v22
	s_nop 1
	v_cndmask_b32_e64 v22, -|v22|, v24, s[0:1]
	v_not_b32_e32 v24, v23
	v_cmp_gt_i32_e64 s[0:1], 0, v23
	v_and_b32_e32 v22, 0xffffff80, v22
	v_sub_u32_e32 v22, v22, v2
	v_cndmask_b32_e64 v23, -|v23|, v24, s[0:1]
	ds_read2_b32 v[24:25], v3 offset0:20 offset1:21
	v_and_b32_e32 v23, 0xffffff80, v23
	v_sub_u32_e32 v23, v23, v2
	v_add_u32_e32 v22, 0x6d, v22
	v_add_u32_e32 v23, 0x6c, v23
	s_waitcnt lgkmcnt(0)
	v_not_b32_e32 v26, v24
	v_cmp_gt_i32_e64 s[0:1], 0, v24
	s_nop 1
	v_cndmask_b32_e64 v24, -|v24|, v26, s[0:1]
	v_and_b32_e32 v24, 0xffffff80, v24
	v_sub_u32_e32 v24, v24, v2
	v_add_u32_e32 v26, 0x6b, v24
	v_not_b32_e32 v24, v25
	v_cmp_gt_i32_e64 s[0:1], 0, v25
	s_nop 1
	v_cndmask_b32_e64 v24, -|v25|, v24, s[0:1]
	v_and_b32_e32 v24, 0xffffff80, v24
	v_sub_u32_e32 v24, v24, v2
	v_add_u32_e32 v27, 0x6a, v24
	ds_read2_b32 v[24:25], v3 offset0:22 offset1:23
	s_waitcnt lgkmcnt(0)
	v_not_b32_e32 v28, v24
	v_cmp_gt_i32_e64 s[0:1], 0, v24
	s_nop 1
	v_cndmask_b32_e64 v24, -|v24|, v28, s[0:1]
	v_and_b32_e32 v24, 0xffffff80, v24
	v_sub_u32_e32 v24, v24, v2
	v_add_u32_e32 v28, 0x69, v24
	v_not_b32_e32 v24, v25
	v_cmp_gt_i32_e64 s[0:1], 0, v25
	s_nop 1
	v_cndmask_b32_e64 v24, -|v25|, v24, s[0:1]
	v_and_b32_e32 v24, 0xffffff80, v24
	v_sub_u32_e32 v24, v24, v2
	v_add_u32_e32 v29, 0x68, v24
	ds_read2_b32 v[24:25], v3 offset0:24 offset1:25
	s_waitcnt lgkmcnt(0)
	v_not_b32_e32 v30, v24
	v_cmp_gt_i32_e64 s[0:1], 0, v24
	s_nop 1
	v_cndmask_b32_e64 v24, -|v24|, v30, s[0:1]
	v_and_b32_e32 v24, 0xffffff80, v24
	v_sub_u32_e32 v24, v24, v2
	v_add_u32_e32 v30, 0x67, v24
	v_not_b32_e32 v24, v25
	v_cmp_gt_i32_e64 s[0:1], 0, v25
	s_nop 1
	v_cndmask_b32_e64 v24, -|v25|, v24, s[0:1]
	v_and_b32_e32 v24, 0xffffff80, v24
	v_sub_u32_e32 v24, v24, v2
	v_add_u32_e32 v31, 0x66, v24
	ds_read2_b32 v[24:25], v3 offset0:26 offset1:27
	s_waitcnt lgkmcnt(0)
	v_not_b32_e32 v32, v24
	v_cmp_gt_i32_e64 s[0:1], 0, v24
	s_nop 1
	v_cndmask_b32_e64 v24, -|v24|, v32, s[0:1]
	v_and_b32_e32 v24, 0xffffff80, v24
	v_sub_u32_e32 v24, v24, v2
	v_add_u32_e32 v32, 0x65, v24
	v_not_b32_e32 v24, v25
	v_cmp_gt_i32_e64 s[0:1], 0, v25
	s_nop 1
	v_cndmask_b32_e64 v24, -|v25|, v24, s[0:1]
	v_and_b32_e32 v24, 0xffffff80, v24
	v_sub_u32_e32 v24, v24, v2
	v_add_u32_e32 v33, 0x64, v24
	ds_read2_b32 v[24:25], v3 offset0:28 offset1:29
	s_waitcnt lgkmcnt(0)
	v_not_b32_e32 v34, v24
	v_cmp_gt_i32_e64 s[0:1], 0, v24
	s_nop 1
	v_cndmask_b32_e64 v24, -|v24|, v34, s[0:1]
	v_and_b32_e32 v24, 0xffffff80, v24
	v_sub_u32_e32 v24, v24, v2
	v_add_u32_e32 v34, 0x63, v24
	v_not_b32_e32 v24, v25
	v_cmp_gt_i32_e64 s[0:1], 0, v25
	s_nop 1
	v_cndmask_b32_e64 v24, -|v25|, v24, s[0:1]
	v_and_b32_e32 v24, 0xffffff80, v24
	v_sub_u32_e32 v24, v24, v2
	v_add_u32_e32 v35, 0x62, v24
	ds_read2_b32 v[24:25], v3 offset0:30 offset1:31
	s_waitcnt lgkmcnt(0)
	v_not_b32_e32 v3, v24
	v_cmp_gt_i32_e64 s[0:1], 0, v24
	s_nop 1
	v_cndmask_b32_e64 v3, -|v24|, v3, s[0:1]
	v_not_b32_e32 v24, v25
	v_cmp_gt_i32_e64 s[0:1], 0, v25
	v_and_b32_e32 v3, 0xffffff80, v3
	v_sub_u32_e32 v3, v3, v2
	v_cndmask_b32_e64 v24, -|v25|, v24, s[0:1]
	v_and_b32_e32 v24, 0xffffff80, v24
	v_sub_u32_e32 v2, v24, v2
	v_add_u32_e32 v3, 0x61, v3
	v_add_u32_e32 v2, 0x60, v2
	v_max_u32_e32 v24, v4, v5
	v_min_u32_e32 v4, v4, v5
	v_max_u32_e32 v5, v7, v6
	v_min_u32_e32 v6, v7, v6
	v_max_u32_e32 v7, v8, v9
	v_min_u32_e32 v8, v8, v9
	v_max_u32_e32 v9, v11, v10
	v_min_u32_e32 v10, v11, v10
	v_max_u32_e32 v11, v12, v13
	v_min_u32_e32 v12, v12, v13
	v_max_u32_e32 v13, v15, v14
	v_min_u32_e32 v14, v15, v14
	v_max_u32_e32 v15, v16, v17
	v_min_u32_e32 v16, v16, v17
	v_max_u32_e32 v17, v19, v18
	v_min_u32_e32 v18, v19, v18
	v_max_u32_e32 v19, v20, v21
	v_min_u32_e32 v20, v20, v21
	v_max_u32_e32 v21, v23, v22
	v_min_u32_e32 v22, v23, v22
	v_max_u32_e32 v23, v26, v27
	v_min_u32_e32 v25, v26, v27
	v_max_u32_e32 v26, v29, v28
	v_min_u32_e32 v27, v29, v28
	v_max_u32_e32 v28, v30, v31
	v_min_u32_e32 v29, v30, v31
	v_max_u32_e32 v30, v33, v32
	v_min_u32_e32 v31, v33, v32
	v_max_u32_e32 v32, v34, v35
	v_min_u32_e32 v33, v34, v35
	v_max_u32_e32 v34, v2, v3
	v_min_u32_e32 v2, v2, v3
	v_max_u32_e32 v3, v24, v6
	v_min_u32_e32 v6, v24, v6
	v_max_u32_e32 v24, v4, v5
	v_min_u32_e32 v4, v4, v5
	v_max_u32_e32 v5, v10, v7
	v_min_u32_e32 v7, v10, v7
	v_max_u32_e32 v10, v9, v8
	v_min_u32_e32 v8, v9, v8
	v_max_u32_e32 v9, v11, v14
	v_min_u32_e32 v11, v11, v14
	v_max_u32_e32 v14, v12, v13
	v_min_u32_e32 v12, v12, v13
	v_max_u32_e32 v13, v18, v15
	v_min_u32_e32 v15, v18, v15
	v_max_u32_e32 v18, v17, v16
	v_min_u32_e32 v16, v17, v16
	v_max_u32_e32 v17, v19, v22
	v_min_u32_e32 v19, v19, v22
	v_max_u32_e32 v22, v20, v21
; #define CE_DESC(a_, b_) do { const unsigned hi_ = max(x[a_], x[b_]), lo_ = min(x[a_], x[b_]); x[a_] = hi_; x[b_] = lo_; } while (0)
; __device__ __forceinline__ void peer_score_unit(const Frame& F, int l, int unit) {
;     ...
; #pragma unroll
;         for (int k = 2; k <= 16; k <<= 1)
; #pragma unroll
;             for (int j = k >> 1; j > 0; j >>= 1)
; #pragma unroll
;                 for (int i = 0; i < 32; ++i) { const int l2 = i ^ j; if (l2 > i) { if ((i & k) == 0) CE_DESC(i, l2); else CE_DESC(l2, i); } }
	v_min_u32_e32 v20, v20, v21
	v_max_u32_e32 v21, v27, v23
	v_min_u32_e32 v23, v27, v23
	v_max_u32_e32 v27, v26, v25
	v_min_u32_e32 v25, v26, v25
	v_max_u32_e32 v26, v28, v31
	v_min_u32_e32 v28, v28, v31
	v_max_u32_e32 v31, v29, v30
	v_min_u32_e32 v29, v29, v30
	v_max_u32_e32 v30, v2, v32
	v_min_u32_e32 v2, v2, v32
	v_max_u32_e32 v32, v34, v33
	v_min_u32_e32 v33, v34, v33
	v_max_u32_e32 v34, v3, v24
	v_min_u32_e32 v3, v3, v24
	v_max_u32_e32 v24, v6, v4
	v_min_u32_e32 v4, v6, v4
	v_max_u32_e32 v6, v8, v7
	v_min_u32_e32 v7, v8, v7
	v_max_u32_e32 v8, v10, v5
	v_min_u32_e32 v5, v10, v5
	v_max_u32_e32 v10, v9, v14
	v_min_u32_e32 v9, v9, v14
	v_max_u32_e32 v14, v11, v12
	v_min_u32_e32 v11, v11, v12
	v_max_u32_e32 v12, v16, v15
	v_min_u32_e32 v15, v16, v15
	v_max_u32_e32 v16, v18, v13
	v_min_u32_e32 v13, v18, v13
	v_max_u32_e32 v18, v17, v22
	v_min_u32_e32 v17, v17, v22
	v_max_u32_e32 v22, v19, v20
	v_min_u32_e32 v19, v19, v20
	v_max_u32_e32 v20, v25, v23
	v_min_u32_e32 v23, v25, v23
	v_max_u32_e32 v25, v27, v21
	v_min_u32_e32 v21, v27, v21
	v_max_u32_e32 v27, v26, v31
	v_min_u32_e32 v26, v26, v31
	v_max_u32_e32 v31, v28, v29
	v_min_u32_e32 v28, v28, v29
	v_max_u32_e32 v29, v33, v2
	v_min_u32_e32 v2, v33, v2
	v_max_u32_e32 v33, v32, v30
	v_min_u32_e32 v30, v32, v30
	v_max_u32_e32 v32, v34, v7
	v_min_u32_e32 v7, v34, v7
	v_max_u32_e32 v34, v3, v6
	v_min_u32_e32 v3, v3, v6
	v_max_u32_e32 v6, v24, v5
	v_min_u32_e32 v5, v24, v5
	v_max_u32_e32 v24, v4, v8
	v_min_u32_e32 v4, v4, v8
	v_max_u32_e32 v8, v15, v10
	v_min_u32_e32 v10, v15, v10
	v_max_u32_e32 v15, v12, v9
	v_min_u32_e32 v9, v12, v9
	v_max_u32_e32 v12, v13, v14
	v_min_u32_e32 v13, v13, v14
	v_max_u32_e32 v14, v16, v11
	v_min_u32_e32 v11, v16, v11
	v_max_u32_e32 v16, v18, v23
	v_min_u32_e32 v18, v18, v23
	v_max_u32_e32 v23, v17, v20
	v_min_u32_e32 v17, v17, v20
	v_max_u32_e32 v20, v22, v21
	v_min_u32_e32 v21, v22, v21
	v_max_u32_e32 v22, v19, v25
	v_min_u32_e32 v19, v19, v25
	v_max_u32_e32 v25, v2, v27
	v_min_u32_e32 v2, v2, v27
	v_max_u32_e32 v27, v29, v26
	v_min_u32_e32 v26, v29, v26
	v_max_u32_e32 v29, v30, v31
	v_min_u32_e32 v30, v30, v31
	v_max_u32_e32 v31, v33, v28
	v_min_u32_e32 v28, v33, v28
	v_max_u32_e32 v33, v32, v6
	v_min_u32_e32 v6, v32, v6
	v_max_u32_e32 v32, v34, v24
	v_min_u32_e32 v24, v34, v24
	v_max_u32_e32 v34, v7, v5
	v_min_u32_e32 v5, v7, v5
	v_max_u32_e32 v7, v3, v4
	v_min_u32_e32 v3, v3, v4
	v_max_u32_e32 v4, v13, v10
	v_min_u32_e32 v10, v13, v10
	v_max_u32_e32 v13, v11, v9
	v_min_u32_e32 v9, v11, v9
	v_max_u32_e32 v11, v12, v8
	v_min_u32_e32 v8, v12, v8
	v_max_u32_e32 v12, v14, v15
	v_min_u32_e32 v14, v14, v15
	v_max_u32_e32 v15, v16, v20
	v_min_u32_e32 v16, v16, v20
	v_max_u32_e32 v20, v23, v22
	v_min_u32_e32 v22, v23, v22
	v_max_u32_e32 v23, v18, v21
	v_min_u32_e32 v18, v18, v21
	v_max_u32_e32 v21, v17, v19
	v_min_u32_e32 v17, v17, v19
	v_max_u32_e32 v19, v30, v2
	v_min_u32_e32 v2, v30, v2
	v_max_u32_e32 v30, v28, v26
	v_min_u32_e32 v26, v28, v26
	v_max_u32_e32 v28, v29, v25
	v_min_u32_e32 v25, v29, v25
	v_max_u32_e32 v29, v31, v27
	v_min_u32_e32 v27, v31, v27
	v_max_u32_e32 v31, v33, v32
	v_min_u32_e32 v32, v33, v32
	v_max_u32_e32 v33, v6, v24
	v_min_u32_e32 v6, v6, v24
	v_max_u32_e32 v24, v34, v7
	v_min_u32_e32 v7, v34, v7
	v_max_u32_e32 v34, v5, v3
	v_min_u32_e32 v3, v5, v3
	v_max_u32_e32 v5, v9, v10
	v_min_u32_e32 v9, v9, v10
	v_max_u32_e32 v10, v13, v4
	v_min_u32_e32 v4, v13, v4
	v_max_u32_e32 v13, v14, v8
	v_min_u32_e32 v8, v14, v8
	v_max_u32_e32 v14, v12, v11
	v_min_u32_e32 v11, v12, v11
	v_max_u32_e32 v12, v15, v20
	v_min_u32_e32 v15, v15, v20
	v_max_u32_e32 v20, v16, v22
	v_min_u32_e32 v16, v16, v22
	v_max_u32_e32 v22, v23, v21
	v_min_u32_e32 v21, v23, v21
	v_max_u32_e32 v23, v18, v17
	v_min_u32_e32 v17, v18, v17
	v_max_u32_e32 v18, v26, v2
	v_min_u32_e32 v2, v26, v2
	v_max_u32_e32 v26, v30, v19
	v_min_u32_e32 v19, v30, v19
	v_max_u32_e32 v30, v27, v25
	v_min_u32_e32 v25, v27, v25
	v_max_u32_e32 v27, v29, v28
	v_min_u32_e32 v28, v29, v28
	v_max_u32_e32 v29, v31, v9
	v_min_u32_e32 v9, v31, v9
	v_max_u32_e32 v31, v32, v5
	v_min_u32_e32 v5, v32, v5
	v_max_u32_e32 v32, v33, v4
	v_min_u32_e32 v4, v33, v4
	v_max_u32_e32 v33, v6, v10
	v_min_u32_e32 v6, v6, v10
	v_max_u32_e32 v10, v24, v8
	v_min_u32_e32 v8, v24, v8
	v_max_u32_e32 v24, v7, v13
	v_min_u32_e32 v7, v7, v13
	v_max_u32_e32 v13, v34, v11
	v_min_u32_e32 v11, v34, v11
	v_max_u32_e32 v34, v3, v14
	v_min_u32_e32 v3, v3, v14
	v_max_u32_e32 v14, v2, v12
	v_min_u32_e32 v2, v2, v12
	v_max_u32_e32 v12, v18, v15
	v_min_u32_e32 v15, v18, v15
	v_max_u32_e32 v18, v19, v20
	v_min_u32_e32 v19, v19, v20
	v_max_u32_e32 v20, v26, v16
	v_min_u32_e32 v16, v26, v16
	v_max_u32_e32 v26, v25, v22
	v_min_u32_e32 v22, v25, v22
	v_max_u32_e32 v25, v30, v21
	v_min_u32_e32 v21, v30, v21
	v_max_u32_e32 v30, v28, v23
	v_min_u32_e32 v23, v28, v23
	v_max_u32_e32 v28, v27, v17
	v_min_u32_e32 v17, v27, v17
	v_max_u32_e32 v27, v29, v10
	v_min_u32_e32 v10, v29, v10
	v_max_u32_e32 v29, v31, v24
	v_min_u32_e32 v24, v31, v24
	v_max_u32_e32 v31, v32, v13
	v_min_u32_e32 v13, v32, v13
	v_max_u32_e32 v32, v33, v34
	v_min_u32_e32 v33, v33, v34
	v_max_u32_e32 v34, v9, v8
	v_min_u32_e32 v8, v9, v8
	v_max_u32_e32 v9, v5, v7
	v_min_u32_e32 v5, v5, v7
	v_max_u32_e32 v7, v4, v11
	v_min_u32_e32 v4, v4, v11
	v_max_u32_e32 v11, v6, v3
	v_min_u32_e32 v3, v6, v3
	v_max_u32_e32 v6, v22, v2
	v_min_u32_e32 v2, v22, v2
	v_max_u32_e32 v22, v21, v15
	v_min_u32_e32 v15, v21, v15
	v_max_u32_e32 v21, v23, v19
	v_min_u32_e32 v19, v23, v19
	v_max_u32_e32 v23, v17, v16
	v_min_u32_e32 v16, v17, v16
	v_max_u32_e32 v17, v26, v14
	v_min_u32_e32 v14, v26, v14
	v_max_u32_e32 v26, v25, v12
; #define CE_DESC(a_, b_) do { const unsigned hi_ = max(x[a_], x[b_]), lo_ = min(x[a_], x[b_]); x[a_] = hi_; x[b_] = lo_; } while (0)
; __device__ __forceinline__ void peer_score_unit(const Frame& F, int l, int unit) {
;     ...
; #pragma unroll
;         for (int i = 0; i < 16; ++i) x[i] = max(x[i], x[i + 16]);
; #pragma unroll
;         for (int j = 8; j > 0; j >>= 1)
; #pragma unroll
;             for (int i = 0; i < 16; ++i) { const int l2 = i ^ j; if (l2 > i) CE_DESC(i, l2); }
;     ...
;         MERGE_LEVEL(0xB1);
;         MERGE_LEVEL(0x4E);
	v_min_u32_e32 v12, v25, v12
	v_max_u32_e32 v25, v30, v18
	v_min_u32_e32 v18, v30, v18
	v_max_u32_e32 v30, v28, v20
	v_min_u32_e32 v20, v28, v20
	v_max_u32_e32 v28, v27, v31
	v_min_u32_e32 v27, v27, v31
	v_max_u32_e32 v31, v29, v32
	v_min_u32_e32 v29, v29, v32
	v_max_u32_e32 v32, v10, v13
	v_min_u32_e32 v10, v10, v13
	v_max_u32_e32 v13, v24, v33
	v_min_u32_e32 v24, v24, v33
	v_max_u32_e32 v33, v34, v7
	v_min_u32_e32 v7, v34, v7
	v_max_u32_e32 v34, v9, v11
	v_min_u32_e32 v9, v9, v11
	v_max_u32_e32 v11, v8, v4
	v_min_u32_e32 v4, v8, v4
	v_max_u32_e32 v8, v5, v3
	v_min_u32_e32 v3, v5, v3
	v_max_u32_e32 v5, v19, v2
	v_min_u32_e32 v2, v19, v2
	v_max_u32_e32 v19, v16, v15
	v_min_u32_e32 v15, v16, v15
	v_max_u32_e32 v16, v21, v6
	v_min_u32_e32 v6, v21, v6
	v_max_u32_e32 v21, v23, v22
	v_min_u32_e32 v22, v23, v22
	v_max_u32_e32 v23, v18, v14
	v_min_u32_e32 v14, v18, v14
	v_max_u32_e32 v18, v20, v12
	v_min_u32_e32 v12, v20, v12
	v_max_u32_e32 v20, v25, v17
	v_min_u32_e32 v17, v25, v17
	v_max_u32_e32 v25, v30, v26
	v_min_u32_e32 v26, v30, v26
	v_min_u32_e32 v30, v28, v31
	v_min_u32_e32 v35, v27, v29
	v_min_u32_e32 v36, v32, v13
	v_min_u32_e32 v37, v10, v24
	v_min_u32_e32 v38, v33, v34
	v_min_u32_e32 v39, v7, v9
	v_min_u32_e32 v40, v11, v8
	v_min_u32_e32 v41, v4, v3
	v_min_u32_e32 v42, v15, v2
	v_min_u32_e32 v43, v19, v5
	v_min_u32_e32 v44, v22, v6
	v_min_u32_e32 v45, v21, v16
	v_min_u32_e32 v46, v12, v14
	v_min_u32_e32 v47, v18, v23
	v_min_u32_e32 v51, v26, v17
	v_min_u32_e32 v52, v25, v20
	v_max3_u32 v20, v41, v25, v20
	v_max3_u32 v25, v28, v31, v42
	v_max3_u32 v2, v30, v15, v2
	v_max3_u32 v15, v27, v29, v43
	v_max3_u32 v5, v35, v19, v5
	v_max3_u32 v13, v32, v13, v44
	v_max3_u32 v6, v36, v22, v6
	v_max3_u32 v10, v10, v24, v45
	v_max3_u32 v16, v37, v21, v16
	v_max3_u32 v19, v33, v34, v46
	v_max3_u32 v12, v38, v12, v14
	v_max3_u32 v7, v7, v9, v47
	v_max3_u32 v9, v39, v18, v23
	v_max3_u32 v8, v11, v8, v51
	v_max3_u32 v11, v40, v26, v17
	v_max3_u32 v3, v4, v3, v52
	v_max_u32_e32 v4, v25, v19
	v_min_u32_e32 v14, v25, v19
	v_max_u32_e32 v17, v2, v12
	v_min_u32_e32 v2, v2, v12
	v_max_u32_e32 v12, v15, v7
	v_min_u32_e32 v7, v15, v7
	v_max_u32_e32 v15, v5, v9
	v_min_u32_e32 v5, v5, v9
	v_max_u32_e32 v9, v13, v8
	v_min_u32_e32 v8, v13, v8
	v_max_u32_e32 v13, v6, v11
	v_min_u32_e32 v6, v6, v11
	v_max_u32_e32 v11, v10, v3
	v_min_u32_e32 v3, v10, v3
	v_max_u32_e32 v10, v16, v20
	v_min_u32_e32 v16, v16, v20
	v_max_u32_e32 v18, v4, v9
	v_min_u32_e32 v4, v4, v9
	v_max_u32_e32 v9, v17, v13
	v_min_u32_e32 v13, v17, v13
	v_max_u32_e32 v17, v12, v11
	v_min_u32_e32 v11, v12, v11
	v_max_u32_e32 v12, v15, v10
	v_min_u32_e32 v10, v15, v10
	v_max_u32_e32 v15, v14, v8
	v_min_u32_e32 v8, v14, v8
	v_max_u32_e32 v14, v2, v6
	v_min_u32_e32 v2, v2, v6
	v_max_u32_e32 v6, v7, v3
	v_min_u32_e32 v3, v7, v3
	v_max_u32_e32 v7, v5, v16
	v_min_u32_e32 v5, v5, v16
	v_max_u32_e32 v16, v18, v17
	v_min_u32_e32 v17, v18, v17
	v_max_u32_e32 v18, v9, v12
	v_min_u32_e32 v9, v9, v12
	v_max_u32_e32 v12, v4, v11
	v_min_u32_e32 v4, v4, v11
	v_max_u32_e32 v11, v13, v10
	v_min_u32_e32 v10, v13, v10
	v_max_u32_e32 v13, v15, v6
	v_min_u32_e32 v6, v15, v6
	v_max_u32_e32 v15, v14, v7
	v_min_u32_e32 v7, v14, v7
	v_max_u32_e32 v14, v8, v3
	v_min_u32_e32 v3, v8, v3
	v_max_u32_e32 v8, v2, v5
	v_min_u32_e32 v2, v2, v5
	v_max_u32_e32 v5, v16, v18
	v_min_u32_e32 v16, v16, v18
	v_max_u32_e32 v18, v17, v9
	v_min_u32_e32 v9, v17, v9
	v_max_u32_e32 v17, v12, v11
	v_min_u32_e32 v11, v12, v11
	v_max_u32_e32 v12, v4, v10
	v_min_u32_e32 v4, v4, v10
	v_max_u32_e32 v10, v13, v15
	v_min_u32_e32 v13, v13, v15
	v_max_u32_e32 v15, v6, v7
	v_min_u32_e32 v6, v6, v7
	v_max_u32_e32 v7, v14, v8
	v_min_u32_e32 v8, v14, v8
	v_max_u32_e32 v14, v3, v2
	v_min_u32_e32 v2, v3, v2
	v_max_u32_dpp v19, v8, v18 quad_perm:[1,0,3,2] row_mask:0xf bank_mask:0xf bound_ctrl:1
	v_max_u32_dpp v20, v7, v9 quad_perm:[1,0,3,2] row_mask:0xf bank_mask:0xf bound_ctrl:1
	v_max_u32_dpp v3, v5, v2 quad_perm:[1,0,3,2] row_mask:0xf bank_mask:0xf bound_ctrl:1
	v_max_u32_dpp v2, v2, v5 quad_perm:[1,0,3,2] row_mask:0xf bank_mask:0xf bound_ctrl:1
	v_max_u32_dpp v5, v14, v16 quad_perm:[1,0,3,2] row_mask:0xf bank_mask:0xf bound_ctrl:1
	v_max_u32_dpp v21, v6, v17 quad_perm:[1,0,3,2] row_mask:0xf bank_mask:0xf bound_ctrl:1
	v_max_u32_dpp v22, v15, v11 quad_perm:[1,0,3,2] row_mask:0xf bank_mask:0xf bound_ctrl:1
	v_max_u32_dpp v23, v13, v12 quad_perm:[1,0,3,2] row_mask:0xf bank_mask:0xf bound_ctrl:1
	v_max_u32_dpp v24, v10, v4 quad_perm:[1,0,3,2] row_mask:0xf bank_mask:0xf bound_ctrl:1
	v_max_u32_dpp v4, v4, v10 quad_perm:[1,0,3,2] row_mask:0xf bank_mask:0xf bound_ctrl:1
	v_max_u32_dpp v10, v12, v13 quad_perm:[1,0,3,2] row_mask:0xf bank_mask:0xf bound_ctrl:1
	v_max_u32_dpp v11, v11, v15 quad_perm:[1,0,3,2] row_mask:0xf bank_mask:0xf bound_ctrl:1
	v_max_u32_dpp v6, v17, v6 quad_perm:[1,0,3,2] row_mask:0xf bank_mask:0xf bound_ctrl:1
	v_max_u32_dpp v7, v9, v7 quad_perm:[1,0,3,2] row_mask:0xf bank_mask:0xf bound_ctrl:1
	v_max_u32_dpp v8, v18, v8 quad_perm:[1,0,3,2] row_mask:0xf bank_mask:0xf bound_ctrl:1
	v_max_u32_dpp v9, v16, v14 quad_perm:[1,0,3,2] row_mask:0xf bank_mask:0xf bound_ctrl:1
	v_max_u32_e32 v12, v2, v4
	v_min_u32_e32 v2, v2, v4
	v_max_u32_e32 v4, v5, v10
	v_min_u32_e32 v5, v5, v10
	v_max_u32_e32 v10, v19, v11
	v_min_u32_e32 v11, v19, v11
	v_max_u32_e32 v13, v20, v6
	v_min_u32_e32 v6, v20, v6
	v_max_u32_e32 v14, v21, v7
	v_min_u32_e32 v7, v21, v7
	v_max_u32_e32 v15, v22, v8
	v_min_u32_e32 v8, v22, v8
	v_max_u32_e32 v16, v23, v9
	v_min_u32_e32 v9, v23, v9
	v_max_u32_e32 v17, v24, v3
	v_min_u32_e32 v3, v24, v3
	v_max_u32_e32 v18, v12, v14
	v_min_u32_e32 v12, v12, v14
; __device__ __forceinline__ void peer_score_unit(const Frame& F, int l, int unit) {
;     ...
;         MERGE_LEVEL(0xB1);
;         MERGE_LEVEL(0x4E);
;     ...
;         if (qd == 0) {
	v_max_u32_e32 v14, v4, v15
	v_min_u32_e32 v4, v4, v15
	v_max_u32_e32 v15, v10, v16
	v_min_u32_e32 v10, v10, v16
	v_max_u32_e32 v16, v13, v17
	v_min_u32_e32 v13, v13, v17
	v_max_u32_e32 v17, v2, v7
	v_min_u32_e32 v2, v2, v7
	v_max_u32_e32 v7, v5, v8
	v_min_u32_e32 v5, v5, v8
	v_max_u32_e32 v8, v11, v9
	v_min_u32_e32 v9, v11, v9
	v_max_u32_e32 v11, v6, v3
	v_min_u32_e32 v3, v6, v3
	v_max_u32_e32 v6, v18, v15
	v_min_u32_e32 v15, v18, v15
	v_max_u32_e32 v18, v14, v16
	v_min_u32_e32 v14, v14, v16
	v_max_u32_e32 v16, v12, v10
	v_min_u32_e32 v10, v12, v10
	v_max_u32_e32 v12, v4, v13
	v_min_u32_e32 v19, v4, v13
	v_max_u32_e32 v20, v17, v8
	v_min_u32_e32 v8, v17, v8
	v_max_u32_e32 v17, v7, v11
	v_min_u32_e32 v7, v7, v11
	v_max_u32_e32 v21, v2, v9
	v_min_u32_e32 v23, v2, v9
	v_max_u32_e32 v24, v5, v3
	v_min_u32_e32 v25, v5, v3
	v_max_u32_e32 v13, v6, v18
	v_min_u32_e32 v4, v6, v18
	v_max_u32_e32 v11, v15, v14
	v_min_u32_e32 v2, v15, v14
	v_max_u32_e32 v14, v16, v12
	v_min_u32_e32 v5, v16, v12
	v_max_u32_e32 v12, v10, v19
	v_min_u32_e32 v3, v10, v19
	v_max_u32_e32 v19, v20, v17
	v_min_u32_e32 v9, v20, v17
	v_max_u32_e32 v17, v8, v7
	v_min_u32_e32 v6, v8, v7
	v_max_u32_e32 v22, v21, v24
	v_min_u32_e32 v10, v21, v24
	v_max_u32_e32 v18, v23, v25
	v_min_u32_e32 v7, v23, v25
	v_mov_b32_e32 v8, v201
	v_mov_b32_e32 v20, v201
	v_mov_b32_e32 v15, v201
	v_mov_b32_e32 v24, v201
	v_mov_b32_e32 v16, v201
	v_mov_b32_e32 v25, v201
	v_mov_b32_e32 v23, v201
	v_mov_b32_e32 v29, v201
	v_mov_b32_e32 v21, v201
	v_mov_b32_e32 v28, v201
	v_mov_b32_e32 v26, v201
	v_mov_b32_e32 v31, v201
	v_mov_b32_e32 v27, v201
	v_mov_b32_e32 v32, v201
	v_mov_b32_e32 v30, v201
	v_mov_b32_e32 v33, v201
	v_mov_b32_dpp v8, v13 quad_perm:[2,3,0,1] row_mask:0xf bank_mask:0xf
	v_mov_b32_dpp v20, v4 quad_perm:[2,3,0,1] row_mask:0xf bank_mask:0xf
	v_mov_b32_dpp v15, v11 quad_perm:[2,3,0,1] row_mask:0xf bank_mask:0xf
	v_mov_b32_dpp v24, v2 quad_perm:[2,3,0,1] row_mask:0xf bank_mask:0xf
	v_mov_b32_dpp v16, v14 quad_perm:[2,3,0,1] row_mask:0xf bank_mask:0xf
	v_mov_b32_dpp v25, v5 quad_perm:[2,3,0,1] row_mask:0xf bank_mask:0xf
	v_mov_b32_dpp v23, v12 quad_perm:[2,3,0,1] row_mask:0xf bank_mask:0xf
	v_mov_b32_dpp v29, v3 quad_perm:[2,3,0,1] row_mask:0xf bank_mask:0xf
	v_mov_b32_dpp v21, v19 quad_perm:[2,3,0,1] row_mask:0xf bank_mask:0xf
	v_mov_b32_dpp v28, v9 quad_perm:[2,3,0,1] row_mask:0xf bank_mask:0xf
	v_mov_b32_dpp v26, v17 quad_perm:[2,3,0,1] row_mask:0xf bank_mask:0xf
	v_mov_b32_dpp v31, v6 quad_perm:[2,3,0,1] row_mask:0xf bank_mask:0xf
	v_mov_b32_dpp v27, v22 quad_perm:[2,3,0,1] row_mask:0xf bank_mask:0xf
	v_mov_b32_dpp v32, v10 quad_perm:[2,3,0,1] row_mask:0xf bank_mask:0xf
	v_mov_b32_dpp v30, v18 quad_perm:[2,3,0,1] row_mask:0xf bank_mask:0xf
	v_mov_b32_dpp v33, v7 quad_perm:[2,3,0,1] row_mask:0xf bank_mask:0xf
	s_and_saveexec_b64 s[0:1], vcc
	s_cbranch_execz .LBB0_2049
; __device__ __forceinline__ void peer_score_unit(const Frame& F, int l, int unit) {
;     ...
;         MERGE_LEVEL(0xB1);
;         MERGE_LEVEL(0x4E);
;     ...
;         if (qd == 0) {
; #pragma unroll
;             for (int k = 0; k < 16; ++k) { const int n = 127 - (int)(x[k] & 127u); SI[row * 16 + k] = n; SV[row * 16 + k] = S[row * 129 + n]; }
;         }
	v_max_u32_e32 v13, v13, v33
	v_max_u32_e32 v19, v19, v29
	v_max_u32_e32 v14, v14, v31
	v_max_u32_e32 v22, v22, v24
	v_max_u32_e32 v11, v11, v32
	v_max_u32_e32 v17, v17, v25
	v_max_u32_e32 v12, v12, v28
	v_max_u32_e32 v18, v18, v20
	v_max_u32_e32 v30, v4, v30
	v_max_u32_e32 v9, v9, v23
	v_max_u32_e32 v26, v5, v26
	v_max_u32_e32 v10, v10, v15
	v_max_u32_e32 v27, v2, v27
	v_max_u32_e32 v6, v6, v16
	v_max_u32_e32 v21, v3, v21
	v_max_u32_e32 v7, v7, v8
	v_min_u32_e32 v29, v13, v19
	v_min_u32_e32 v24, v14, v22
	v_min_u32_e32 v25, v11, v17
	v_min_u32_e32 v20, v12, v18
	v_min_u32_e32 v23, v30, v9
	v_min_u32_e32 v15, v26, v10
	v_min_u32_e32 v16, v27, v6
	v_min_u32_e32 v8, v21, v7
	v_min_u32_e32 v31, v29, v24
	v_min_u32_e32 v28, v25, v20
	v_min_u32_e32 v4, v23, v15
	v_min_u32_e32 v5, v16, v8
	v_max_u32_e32 v24, v29, v24
	v_max_u32_e32 v20, v25, v20
	v_max_u32_e32 v15, v23, v15
	v_max_u32_e32 v8, v16, v8
	v_min_u32_e32 v25, v24, v20
	v_min_u32_e32 v16, v15, v8
	v_max_u32_e32 v20, v24, v20
	v_max_u32_e32 v8, v15, v8
	v_max_u32_e32 v13, v13, v19
	v_max_u32_e32 v14, v14, v22
	v_max_u32_e32 v11, v11, v17
	v_max_u32_e32 v12, v12, v18
	v_max_u32_e32 v9, v30, v9
	v_max_u32_e32 v10, v26, v10
	v_max_u32_e32 v6, v27, v6
	v_max_u32_e32 v7, v21, v7
	v_min_u32_e32 v15, v20, v8
	v_max_u32_e32 v8, v20, v8
	v_min_u32_e32 v19, v13, v14
	v_min_u32_e32 v17, v11, v12
	v_min_u32_e32 v20, v9, v10
	v_min_u32_e32 v21, v6, v7
	v_max_u32_e32 v13, v13, v14
	v_max_u32_e32 v11, v11, v12
	v_max_u32_e32 v9, v9, v10
	v_max_u32_e32 v6, v6, v7
	v_min_u32_e32 v12, v13, v11
	v_min_u32_e32 v7, v9, v6
	v_min_u32_e32 v10, v12, v7
	v_max_u32_e32 v12, v12, v7
	v_max_u32_e32 v7, v13, v11
	v_max_u32_e32 v6, v9, v6
	v_min_u32_e32 v9, v7, v6
	v_max_u32_e32 v6, v7, v6
	v_xor_b32_e32 v6, -1, v6
	v_and_b32_e32 v6, 0x7f, v6
	v_xor_b32_e32 v7, -1, v9
	v_lshl_add_u32 v9, v6, 2, v0
	ds_read_b32 v60, v9
	v_lshlrev_b32_e32 v11, 6, v1
	v_add_u32_e32 v1, s58, v11
	v_and_b32_e32 v7, 0x7f, v7
	v_add_u32_e32 v13, s57, v11
	ds_write_b64 v13, v[6:7]
	v_lshl_add_u32 v6, v7, 2, v0
	ds_read_b32 v61, v6
	v_min_u32_e32 v18, v19, v17
	v_max_u32_e32 v17, v19, v17
	v_max_u32_e32 v19, v20, v21
	v_min_u32_e32 v22, v20, v21
	v_or_b32_e32 v6, 8, v11
	v_add_u32_e32 v9, s57, v6
	v_add_u32_e32 v13, s58, v6
	v_xor_b32_e32 v6, -1, v10
	v_xor_b32_e32 v10, -1, v12
	v_and_b32_e32 v7, 0x7f, v6
	v_and_b32_e32 v6, 0x7f, v10
	v_lshl_add_u32 v10, v6, 2, v0
	ds_read_b32 v62, v10
	ds_write_b64 v9, v[6:7]
	v_lshl_add_u32 v6, v7, 2, v0
	ds_read_b32 v63, v6
	v_min_u32_e32 v20, v17, v19
	v_max_u32_e32 v17, v17, v19
	v_xor_b32_e32 v12, -1, v17
	v_min_u32_e32 v24, v18, v22
	v_or_b32_e32 v6, 16, v11
	v_add_u32_e32 v9, s57, v6
	v_add_u32_e32 v10, s58, v6
	v_xor_b32_e32 v6, -1, v20
	v_and_b32_e32 v7, 0x7f, v6
	v_and_b32_e32 v6, 0x7f, v12
	v_lshl_add_u32 v12, v6, 2, v0
	ds_read_b32 v64, v12
	ds_write_b64 v9, v[6:7]
	v_lshl_add_u32 v6, v7, 2, v0
	ds_read_b32 v65, v6
	v_max_u32_e32 v18, v18, v22
	v_xor_b32_e32 v12, -1, v18
	v_xor_b32_e32 v8, -1, v8
	v_min_u32_e32 v23, v25, v16
	v_or_b32_e32 v6, 24, v11
	v_add_u32_e32 v9, s57, v6
	v_add_u32_e32 v10, s58, v6
	v_xor_b32_e32 v6, -1, v24
	v_and_b32_e32 v7, 0x7f, v6
	v_and_b32_e32 v6, 0x7f, v12
	v_lshl_add_u32 v12, v6, 2, v0
	ds_read_b32 v66, v12
	ds_write_b64 v9, v[6:7]
	v_lshl_add_u32 v6, v7, 2, v0
	ds_read_b32 v67, v6
	v_max_u32_e32 v16, v25, v16
	v_min_u32_e32 v32, v31, v28
	v_min_u32_e32 v2, v4, v5
	v_max_u32_e32 v28, v31, v28
	v_or_b32_e32 v6, 32, v11
	v_add_u32_e32 v9, s57, v6
	v_add_u32_e32 v10, s58, v6
	v_xor_b32_e32 v6, -1, v15
	v_and_b32_e32 v7, 0x7f, v6
	v_and_b32_e32 v6, 0x7f, v8
	v_lshl_add_u32 v8, v6, 2, v0
	ds_read_b32 v68, v8
	ds_write_b64 v9, v[6:7]
	v_lshl_add_u32 v6, v7, 2, v0
	ds_read_b32 v69, v6
	v_xor_b32_e32 v10, -1, v16
	v_max_u32_e32 v4, v4, v5
	v_min_u32_e32 v5, v28, v4
	v_max_u32_e32 v4, v28, v4
	v_or_b32_e32 v6, 40, v11
	v_add_u32_e32 v8, s57, v6
	v_add_u32_e32 v9, s58, v6
	v_xor_b32_e32 v6, -1, v23
	v_and_b32_e32 v7, 0x7f, v6
	v_and_b32_e32 v6, 0x7f, v10
	v_lshl_add_u32 v10, v6, 2, v0
	ds_read_b32 v70, v10
	ds_write_b64 v8, v[6:7]
	v_lshl_add_u32 v6, v7, 2, v0
	ds_read_b32 v71, v6
	v_xor_b32_e32 v4, -1, v4
	v_and_b32_e32 v4, 0x7f, v4
	v_lshl_add_u32 v8, v4, 2, v0
	v_xor_b32_e32 v5, -1, v5
	ds_read_b32 v72, v8
	v_or_b32_e32 v6, 48, v11
	v_add_u32_e32 v7, s57, v6
	v_add_u32_e32 v6, s58, v6
	v_and_b32_e32 v5, 0x7f, v5
	ds_write_b64 v7, v[4:5]
	v_lshl_add_u32 v4, v5, 2, v0
	ds_read_b32 v73, v4
	v_min_u32_e32 v3, v32, v2
	v_max_u32_e32 v2, v32, v2
	v_xor_b32_e32 v2, -1, v2
	v_and_b32_e32 v2, 0x7f, v2
	v_lshl_add_u32 v6, v2, 2, v0
	ds_read_b32 v74, v6
	v_or_b32_e32 v4, 56, v11
	v_xor_b32_e32 v3, -1, v3
	v_add_u32_e32 v5, s57, v4
	v_add_u32_e32 v4, s58, v4
	v_and_b32_e32 v3, 0x7f, v3
	ds_write_b64 v5, v[2:3]
	v_lshl_add_u32 v0, v3, 2, v0
	ds_read_b32 v75, v0
	s_waitcnt lgkmcnt(0)
	ds_write_b32 v1, v60
	ds_write_b32 v1, v61 offset:4
	ds_write_b32 v1, v62 offset:8
	ds_write_b32 v1, v63 offset:12
	ds_write_b32 v1, v64 offset:16
	ds_write_b32 v1, v65 offset:20
	ds_write_b32 v1, v66 offset:24
	ds_write_b32 v1, v67 offset:28
	ds_write_b32 v1, v68 offset:32
	ds_write_b32 v1, v69 offset:36
	ds_write_b32 v1, v70 offset:40
	ds_write_b32 v1, v71 offset:44
	ds_write_b32 v1, v72 offset:48
	ds_write_b32 v1, v73 offset:52
	ds_write_b32 v1, v74 offset:56
	ds_write_b32 v1, v75 offset:60
